# v26 + peeled first-segment wait in the two M1 bf16 GEMMs relaxed vmcnt(0)->vmcnt(6) (16 stores follow every load) + two compiler-inserted vmcnt(0) drains removed from the F1 int8 phase prologue DMA se
# speedup vs baseline: 1.0121x; 1.0014x over previous
;     __device__ __forceinline__ const char* pa(const Gemm& g, const Unit& u, size_t tstep) const { return (const char*)g.A + (size_t)u.pm * tstep; }
;     __device__ __forceinline__ const char* pb(const Gemm& g, const Unit& u, size_t tstep) const { return (const char*)g.Bt + (size_t)u.pn * tstep; }
;     __device__ __forceinline__ const char* pa(const Gemm& g, const Unit& u, size_t tstep) const { return (const char*)g.A + (size_t)(u.pn >> 1) * 512 + (size_t)u.pm * tstep; }
; #define PG8_BAR __builtin_amdgcn_s_barrier()
;     int tid_l = threadIdx.x; asm volatile("" : "+v"(tid_l)); const int tid = tid_l, wid = __builtin_amdgcn_readfirstlane(tid >> 6), lane = tid & 63, wr = wid >> 2, wc = wid & 3, fr = lane & 15, fq = lane >> 4;
;     const int K = g.K, nt = K / BK;
;     unsigned voffA[2], voffB[2];
; #pragma unroll
;     for (int i = 0; i < 2; ++i) { int R, C; stage_rc(tid * 16 + i * 8192, R, C); const int Rb = Epi::PERM ? ((R & ~31) + perm32(R & 31)) : R;
;         voffA[i] = (unsigned)(R * (LDA ? LDA : K) + C) * 2u; voffB[i] = (unsigned)(Rb * K + C) * 2u; }
;     const size_t kstep = (size_t)(BK * 2);
;     const size_t hstepB = (size_t)HALF * K * 2, hstepA = LDA ? (size_t)HALF * LDA * 2 : hstepB;
;     const size_t tstepA = 2 * hstepA, tstepB = 2 * hstepB;
;     const unsigned ldsw = (unsigned)wid * 1024u;
;     const int aoff = lds_byte(wr * 64 + fr, fq * 8), boff = lds_byte(wc * 32 + fr, fq * 8);
;     ...
;     Unit cur, nxt; int ui = 0;
;     if (!S.next(0, cur)) return;
;     f32x4 acc[2][2][4][2];
; #pragma unroll
;     for (int a = 0; a < 2; ++a)
; #pragma unroll
;         for (int b = 0; b < 2; ++b)
; #pragma unroll
;             for (int m = 0; m < 4; ++m)
; #pragma unroll
;                 for (int n = 0; n < 2; ++n) acc[a][b][m][n] = (f32x4){0.f, 0.f, 0.f, 0.f};
;     bf16x8 At[4][2], B0[2][2], B1[2][2];
;     const char* cA = S.pa(g, cur, tstepA); const char* cB = S.pb(g, cur, tstepB);
;     S.a_ready(cur);
;     if constexpr (SP2) {
;         PG8_STAGE(PG8_SB(0, 0), cB, voffB); PG8_STAGE(PG8_SB(0, 1), cB + hstepB, voffB); PG8_STAGE(PG8_SA(0, 0), cA, voffA); PG8_STAGE(PG8_SA(0, 1), cA + hstepA, voffA);
;         if (wr == 1) PG8_BAR;
;         PG8_WAIT_V(2); PG8_BAR;
;         PG8_STAGE(PG8_SB(1, 0), cB + kstep, voffB); PG8_STAGE(PG8_SA(1, 0), cA + kstep, voffA); PG8_STAGE(PG8_SB(1, 1), cB + hstepB + kstep, voffB);
;         PG8_WAIT_V(6); PG8_BAR;
.LBB0_530:
	v_ashrrev_i32_e32 v3, 31, v11
	v_lshrrev_b32_e32 v3, 26, v3
	v_add_u32_e32 v3, v11, v3
	v_ashrrev_i32_e32 v12, 6, v3
	v_bfe_i32 v3, v11, 27, 1
	v_lshlrev_b32_e32 v2, 4, v11
	v_lshrrev_b32_e32 v3, 22, v3
	v_add_u32_e32 v3, v2, v3
	v_and_b32_e32 v3, 0xfffffc00, v3
	v_sub_u32_e32 v3, v2, v3
	v_lshrrev_b32_e32 v4, 4, v3
	v_bitop3_b32 v3, v4, v3, 32 bitop3:0x6c
	v_ashrrev_i32_e32 v5, 31, v3
	v_lshrrev_b32_e32 v5, 26, v5
	v_add_u32_e32 v5, v3, v5
	v_lshlrev_b32_e32 v4, 3, v12
	v_ashrrev_i32_e32 v13, 6, v5
	v_and_b32_e32 v5, 0xc0, v5
	v_and_b32_e32 v4, -16, v4
	v_sub_u32_e32 v3, v3, v5
	v_add_u32_e32 v4, v13, v4
	v_ashrrev_i16_sdwa v3, v1, sext(v3) dst_sel:DWORD dst_unused:UNUSED_PAD src0_sel:DWORD src1_sel:BYTE_0
	v_lshlrev_b32_e32 v6, 5, v12
	v_bfe_i32 v14, v3, 0, 16
	v_lshlrev_b32_e32 v3, 1, v4
	v_lshrrev_b32_e32 v5, 2, v4
	v_and_b32_e32 v7, 3, v13
	s_mov_b32 s10, 0x1fffe0
	v_and_b32_e32 v6, 32, v6
	v_and_b32_e32 v3, 24, v3
	v_and_b32_e32 v5, 4, v5
	v_and_or_b32 v7, v4, s10, v7
	v_or3_b32 v3, v7, v5, v3
	v_add_lshl_u32 v5, v6, v14, 1
	v_add_u32_e32 v2, 0x2000, v2
	v_lshl_add_u32 v34, v3, 11, v5
	v_ashrrev_i32_e32 v3, 31, v2
	v_lshrrev_b32_e32 v3, 22, v3
	v_add_u32_e32 v3, v2, v3
	v_ashrrev_i32_e32 v15, 10, v3
	v_mul_i32_i24_e32 v3, 0x400, v15
	v_sub_u32_e32 v2, v2, v3
	v_lshrrev_b32_e32 v3, 4, v2
	v_bitop3_b32 v2, v3, v2, 32 bitop3:0x6c
	v_lshl_add_u32 v132, v4, 11, v5
	v_ashrrev_i32_e32 v4, 31, v2
	v_lshrrev_b32_e32 v4, 26, v4
	v_lshlrev_b32_e32 v3, 3, v15
	v_add_u32_e32 v4, v2, v4
	v_and_b32_e32 v3, -16, v3
	v_ashrrev_i32_e32 v16, 6, v4
	v_add_u32_e32 v3, v16, v3
	v_and_b32_e32 v6, 3, v16
	s_ashr_i32 s12, s6, 6
	s_ashr_i32 s8, s6, 8
	v_and_or_b32 v6, v3, s10, v6
	s_lshl_b32 s10, s12, 10
	s_and_b64 s[30:31], s[46:47], exec
	s_cselect_b32 s13, 0, 0x9700000
	s_add_u32 s11, s18, 0x40c00000
	s_addc_u32 s24, s19, 0
	s_add_u32 s79, s9, s13
	v_and_b32_e32 v4, 0xc0, v4
	s_addc_u32 s80, s76, 0
	s_ashr_i32 s63, s62, 31
	s_ashr_i32 s45, s44, 31
	v_sub_u32_e32 v2, v2, v4
	s_lshl_b64 s[30:31], s[62:63], 19
	s_lshl_b64 s[34:35], s[44:45], 19
	v_ashrrev_i16_sdwa v2, v1, sext(v2) dst_sel:DWORD dst_unused:UNUSED_PAD src0_sel:DWORD src1_sel:BYTE_0
	s_add_u32 s66, s79, s34
	v_writelane_b32 v255, s67, 26
	v_lshlrev_b32_e32 v5, 5, v15
	v_bfe_i32 v17, v2, 0, 16
	v_lshlrev_b32_e32 v2, 1, v3
	v_lshrrev_b32_e32 v4, 2, v3
	s_addc_u32 s67, s80, s35
	s_add_i32 s81, s10, 0
	v_and_b32_e32 v5, 32, v5
	v_and_b32_e32 v2, 24, v2
	v_and_b32_e32 v4, 4, v4
	s_add_i32 m0, s81, 0x10000
	v_or3_b32 v2, v6, v4, v2
	v_add_lshl_u32 v4, v5, v17, 1
	global_load_lds_dwordx4 v34, s[66:67]
	s_add_i32 m0, s81, 0x12000
	v_lshl_add_u32 v136, v2, 11, v4
	s_add_u32 s34, s66, 0x40000
	global_load_lds_dwordx4 v136, s[66:67]
	s_addc_u32 s35, s67, 0
	s_add_i32 m0, s81, 0x14000
	v_lshl_add_u32 v134, v3, 11, v4
	global_load_lds_dwordx4 v34, s[34:35]
	s_add_i32 m0, s81, 0x16000
	s_add_u32 s64, s11, s30
	s_addc_u32 s65, s24, s31
	s_add_i32 s82, s81, 0x2000
	global_load_lds_dwordx4 v136, s[34:35]
	s_mov_b32 m0, s81
	s_add_u32 s30, s64, 0x40000
	global_load_lds_dwordx4 v132, s[64:65]
	s_mov_b32 m0, s82
	s_addc_u32 s31, s65, 0
	s_add_i32 s83, s81, 0x4000
	global_load_lds_dwordx4 v134, s[64:65]
	s_mov_b32 m0, s83
	s_add_i32 s84, s81, 0x6000
	global_load_lds_dwordx4 v132, s[30:31]
	s_mov_b32 m0, s84
	v_writelane_b32 v255, s86, 28
	global_load_lds_dwordx4 v134, s[30:31]
	v_mov_b32_e32 v137, v35
	v_mov_b32_e32 v133, v35
	v_mov_b32_e32 v135, v35
	s_cmp_eq_u32 s8, 1
	v_writelane_b32 v255, s87, 29
	v_lshl_add_u64 v[8:9], s[66:67], 0, v[34:35]
	v_lshl_add_u64 v[6:7], s[66:67], 0, v[136:137]
	v_lshl_add_u64 v[2:3], s[64:65], 0, v[132:133]
	s_cselect_b64 s[30:31], -1, 0
	s_cmp_lg_u32 s8, 1
	v_lshl_add_u64 v[4:5], s[64:65], 0, v[134:135]
	s_cbranch_scc1 .LBB0_532
	s_barrier
.LBB0_532:
	s_add_u32 s36, s18, 0x42c00000
	s_addc_u32 s37, s19, 0
	s_add_u32 s50, s18, 0x180000
	s_addc_u32 s51, s19, 0
	s_lshl_b32 s12, s12, 5
	s_and_b32 s42, s12, 0x60
	s_lshl_b32 s15, s8, 13
	s_lshl_b32 s40, s42, 7
	s_cmp_lt_u32 s20, 4
	s_cselect_b64 s[12:13], -1, 0
	s_cmp_eq_u32 s20, 7
	s_cselect_b64 s[34:35], -1, 0
	s_or_b64 s[12:13], s[12:13], s[34:35]
	s_and_b64 s[12:13], s[12:13], exec
	v_readlane_b32 s12, v255, 20
	s_cselect_b32 s85, 0, s12
	s_add_i32 m0, s81, 0x18000
	v_lshl_add_u64 v[8:9], v[8:9], 0, s[22:23]
	s_waitcnt vmcnt(2)
	s_barrier
	global_load_lds_dwordx4 v[8:9], off
	v_lshl_add_u64 v[6:7], v[6:7], 0, s[22:23]
	s_add_i32 m0, s81, 0x1a000
	s_add_i32 s86, s81, 0x8000
	s_add_i32 s87, s81, 0xa000
	global_load_lds_dwordx4 v[6:7], off
	v_lshl_add_u64 v[2:3], v[2:3], 0, s[22:23]
	s_mov_b32 m0, s86
	s_add_u32 s12, s66, 0x40080
	global_load_lds_dwordx4 v[2:3], off
	v_lshl_add_u64 v[2:3], v[4:5], 0, s[22:23]
	s_mov_b32 m0, s87
	s_addc_u32 s13, s67, 0
	global_load_lds_dwordx4 v[2:3], off
	s_add_i32 m0, s81, 0x1c000
	v_lshl_add_u64 v[2:3], s[12:13], 0, v[34:35]
	global_load_lds_dwordx4 v[2:3], off
	v_lshl_add_u64 v[2:3], s[12:13], 0, v[136:137]
	s_add_i32 m0, s81, 0x1e000
	v_div_scale_f32 v6, s[12:13], v10, v10, 1.0
	global_load_lds_dwordx4 v[2:3], off
	v_bfe_u32 v3, v11, 4, 2
	v_rcp_f32_e32 v7, v6
	v_and_b32_e32 v2, 15, v11
	v_lshlrev_b32_e32 v4, 4, v3
	v_lshlrev_b32_e32 v5, 2, v11
	v_lshl_or_b32 v152, s8, 6, v2
	v_lshl_or_b32 v4, v2, 6, v4
	v_and_b32_e32 v5, 32, v5
	v_or_b32_e32 v2, v3, v2
	v_bitop3_b32 v153, v4, s40, v5 bitop3:0xde
	v_cmp_eq_u32_e64 s[40:41], 0, v2
	v_lshlrev_b32_e32 v2, 14, v12
	v_bitop3_b32 v8, v4, s15, v5 bitop3:0xde
	v_fma_f32 v4, -v6, v7, 1.0
	v_and_b32_e32 v2, 0xffff8000, v2
	v_fmac_f32_e32 v7, v4, v7
	v_div_scale_f32 v4, vcc, 1.0, v10, 1.0
	v_lshl_or_b32 v155, v3, 3, s42
	v_lshl_add_u32 v2, v13, 11, v2
	v_and_b32_e32 v3, 1, v12
	v_mul_f32_e32 v5, v4, v7
	v_lshl_or_b32 v2, v3, 6, v2
	v_fma_f32 v9, -v6, v5, v4
	v_lshl_add_u32 v138, v14, 1, v2
	v_lshlrev_b32_e32 v2, 14, v15
	v_fmac_f32_e32 v5, v9, v7
	v_and_b32_e32 v2, 0xffff8000, v2
	v_fma_f32 v4, -v6, v5, v4
	s_waitcnt vmcnt(6)
	v_lshl_add_u32 v2, v16, 11, v2
	v_and_b32_e32 v3, 1, v15
	v_div_fmas_f32 v4, v4, v7, v5
	s_cmpk_lt_u32 s6, 0x100
	v_lshl_or_b32 v2, v3, 6, v2
	v_div_fixup_f32 v154, v4, v10, 1.0
	s_mov_b32 s8, 0
	s_cselect_b64 s[52:53], -1, 0
	s_ashr_i32 s12, s78, 31
	s_ashr_i32 s13, s77, 31
	v_mov_b32_e32 v139, v35
	v_lshl_add_u32 v140, v17, 1, v2
	v_mov_b32_e32 v141, v35
	v_add_u32_e32 v156, 0, v8
	s_barrier
	s_branch .LBB0_535

; #define PG8_STAGE(bufoff, gbase, voff) do { _Pragma("unroll") for (int _i = 0; _i < 2; ++_i) \
;         __builtin_amdgcn_global_load_lds((const unsigned*)((const char*)(gbase) + (voff)[_i]), (PG8_LAS unsigned*)(lds + (bufoff) + ldsw + _i * 8192), 16, 0, 0); } while (0)
; #define PG8_LDA(dst, b, h) do { _Pragma("unroll") for (int m = 0; m < 4; ++m) _Pragma("unroll") for (int k = 0; k < 2; ++k) dst[m][k] = *(const PG8_LAS bf16x8*)(lds + PG8_SA(b, h) + aoff + m * 2048 + k * 1024); } while (0)
; #define PG8_LDB(dst, b, h) do { _Pragma("unroll") for (int n = 0; n < 2; ++n) _Pragma("unroll") for (int k = 0; k < 2; ++k) dst[n][k] = *(const PG8_LAS bf16x8*)(lds + PG8_SB(b, h) + boff + n * 2048 + k * 1024); } while (0)
; #define PG8_WAIT_V(n) asm volatile("s_waitcnt vmcnt(" #n ")" ::: "memory")
; #define PG8_WAIT_L(n) asm volatile("s_waitcnt lgkmcnt(" #n ")" ::: "memory")
; #define PG8_BAR __builtin_amdgcn_s_barrier()
; #define PG8_SCHED __builtin_amdgcn_sched_barrier(0)
;     ...
;             PG8_LDB(B0, 0, 0); PG8_LDB(B1, 0, 1); PG8_SCHED; PG8_LDA(At, 0, 0); PG8_STAGE(PG8_SA(1, 1), a1 + hstepA, voffA);
;             PG8_WAIT_V(8); PG8_WAIT_L(0); PG8_BAR; PG8_MMA(0, 0, At, B0); PG8_MMA(0, 1, At, B1); PG8_BAR; PG8_SCHED;
;             PG8_LDA(At, 0, 1); PG8_STAGE(PG8_SB(0, 0), b2, voffB); PG8_STAGE(PG8_SB(0, 1), b2 + hstepB, voffB); PG8_STAGE(PG8_SA(0, 0), a2, voffA);
;             PG8_WAIT_V(8); PG8_WAIT_L(0); PG8_BAR; PG8_MMA(1, 0, At, B0); PG8_MMA(1, 1, At, B1); PG8_BAR; PG8_SCHED;
.LBB0_922:
	s_ashr_i32 s47, s46, 31
	s_lshl_b64 s[34:35], s[46:47], 20
	s_add_u32 s48, s60, s34
	s_addc_u32 s49, s61, s35
	s_and_b64 s[34:35], s[38:39], exec
	s_cselect_b32 s6, s49, s53
	s_cselect_b32 s15, s48, s52
	s_ashr_i32 s37, s36, 31
	s_lshl_b64 s[34:35], s[36:37], 20
	s_add_u32 s50, s62, s34
	s_addc_u32 s51, s63, s35
	s_and_b64 s[34:35], s[38:39], exec
	s_cselect_b32 s34, s51, s57
	s_cselect_b32 s35, s50, s56
	s_add_u32 s52, s52, 0x80080
	s_addc_u32 s53, s53, 0
	s_add_u32 s37, s56, 0x100
	s_addc_u32 s41, s57, 0
	s_mov_b32 s47, -2
	v_add_u32_e32 v226, 0x10000, v153
	s_add_u32 s56, s52, 0xfff80080
	s_addc_u32 s57, s53, -1
	s_add_i32 s68, 0, 0x10000
	s_cmp_eq_u32 s47, 28
	s_cselect_b32 s59, s6, s57
	s_cselect_b32 s58, s15, s56
	s_cselect_b32 s57, s34, s41
	s_cselect_b32 s56, s35, s37
	s_add_i32 s76, 0, 0x14000
	s_waitcnt vmcnt(6)
	ds_read_b128 v[132:135], v226
	ds_read_b128 v[136:139], v226 offset:1024
	ds_read_b128 v[156:159], v226 offset:2048
	ds_read_b128 v[160:163], v226 offset:3072
	ds_read_b128 v[186:189], v226 offset:16384
	ds_read_b128 v[190:193], v226 offset:17408
	ds_read_b128 v[194:197], v226 offset:18432
	ds_read_b128 v[198:201], v226 offset:19456
	s_add_i32 m0, s10, 0xc000
	ds_read_b128 v[202:205], v155
	ds_read_b128 v[206:209], v155 offset:1024
	ds_read_b128 v[210:213], v155 offset:2048
	ds_read_b128 v[214:217], v155 offset:3072
	ds_read_b128 v[218:221], v155 offset:4096
	ds_read_b128 v[222:225], v155 offset:5120
	ds_read_b128 v[234:237], v155 offset:6144
	ds_read_b128 v[238:241], v155 offset:7168
	global_load_lds_dwordx4 v148, s[52:53]
	s_add_i32 m0, s10, 0xe000
	s_nop 0
	global_load_lds_dwordx4 v150, s[52:53]
	s_waitcnt vmcnt(8)
	s_waitcnt lgkmcnt(0)
	s_barrier
	v_mfma_f32_16x16x32_bf16 v[128:131], v[132:135], v[202:205], 0
	v_mfma_f32_16x16x32_bf16 v[124:127], v[156:159], v[202:205], 0
	v_mfma_f32_16x16x32_bf16 v[112:115], v[132:135], v[210:213], 0
	v_mfma_f32_16x16x32_bf16 v[108:111], v[156:159], v[210:213], 0
	v_mfma_f32_16x16x32_bf16 v[96:99], v[132:135], v[218:221], 0
	v_mfma_f32_16x16x32_bf16 v[92:95], v[156:159], v[218:221], 0
	v_mfma_f32_16x16x32_bf16 v[80:83], v[132:135], v[234:237], 0
	v_mfma_f32_16x16x32_bf16 v[76:79], v[156:159], v[234:237], 0
	v_mfma_f32_16x16x32_bf16 v[128:131], v[136:139], v[206:209], v[128:131]
	v_mfma_f32_16x16x32_bf16 v[124:127], v[160:163], v[206:209], v[124:127]
	v_mfma_f32_16x16x32_bf16 v[112:115], v[136:139], v[214:217], v[112:115]
	v_mfma_f32_16x16x32_bf16 v[108:111], v[160:163], v[214:217], v[108:111]
	v_mfma_f32_16x16x32_bf16 v[96:99], v[136:139], v[222:225], v[96:99]
	v_mfma_f32_16x16x32_bf16 v[92:95], v[160:163], v[222:225], v[92:95]
	v_mfma_f32_16x16x32_bf16 v[80:83], v[136:139], v[238:241], v[80:83]
	v_mfma_f32_16x16x32_bf16 v[76:79], v[160:163], v[238:241], v[76:79]
	v_mfma_f32_16x16x32_bf16 v[120:123], v[186:189], v[202:205], 0
	v_mfma_f32_16x16x32_bf16 v[116:119], v[194:197], v[202:205], 0
	v_mfma_f32_16x16x32_bf16 v[104:107], v[186:189], v[210:213], 0
	v_mfma_f32_16x16x32_bf16 v[100:103], v[194:197], v[210:213], 0
	v_mfma_f32_16x16x32_bf16 v[88:91], v[186:189], v[218:221], 0
	v_mfma_f32_16x16x32_bf16 v[84:87], v[194:197], v[218:221], 0
	v_mfma_f32_16x16x32_bf16 v[72:75], v[186:189], v[234:237], 0
	v_mfma_f32_16x16x32_bf16 v[68:71], v[194:197], v[234:237], 0
	v_mfma_f32_16x16x32_bf16 v[120:123], v[190:193], v[206:209], v[120:123]
	v_mfma_f32_16x16x32_bf16 v[116:119], v[198:201], v[206:209], v[116:119]
	v_mfma_f32_16x16x32_bf16 v[104:107], v[190:193], v[214:217], v[104:107]
	v_mfma_f32_16x16x32_bf16 v[100:103], v[198:201], v[214:217], v[100:103]
	v_mfma_f32_16x16x32_bf16 v[88:91], v[190:193], v[222:225], v[88:91]
	v_mfma_f32_16x16x32_bf16 v[84:87], v[198:201], v[222:225], v[84:87]
	v_mfma_f32_16x16x32_bf16 v[72:75], v[190:193], v[238:241], v[72:75]
	v_mfma_f32_16x16x32_bf16 v[68:71], v[198:201], v[238:241], v[68:71]
	s_barrier
	s_add_i32 s68, s68, s9
	s_mov_b32 m0, s68
	ds_read_b128 v[202:205], v155 offset:16384
	ds_read_b128 v[206:209], v155 offset:17408
	ds_read_b128 v[210:213], v155 offset:18432
	ds_read_b128 v[214:217], v155 offset:19456
	ds_read_b128 v[218:221], v155 offset:20480
	ds_read_b128 v[222:225], v155 offset:21504
	ds_read_b128 v[234:237], v155 offset:22528
	ds_read_b128 v[238:241], v155 offset:23552
	global_load_lds_dwordx4 v142, s[56:57]
	s_add_i32 m0, s68, 0x2000
	s_add_u32 s70, s56, 0x80000
	s_addc_u32 s71, s57, 0
	s_add_i32 s68, s76, s9
	global_load_lds_dwordx4 v146, s[56:57]
	s_mov_b32 m0, s68
	s_add_u32 s98, s58, 0x80
	s_addc_u32 s99, s59, 0
	global_load_lds_dwordx4 v142, s[70:71]
	s_add_i32 m0, s68, 0x2000
	s_nop 0
	global_load_lds_dwordx4 v146, s[70:71]
	s_mov_b32 m0, s10
	s_nop 0
	global_load_lds_dwordx4 v140, s[58:59]
	s_mov_b32 m0, s11
	s_nop 0
	global_load_lds_dwordx4 v144, s[58:59]
	s_waitcnt vmcnt(8)
	s_waitcnt lgkmcnt(0)
	s_barrier
	v_mfma_f32_16x16x32_bf16 v[64:67], v[132:135], v[202:205], 0
	v_mfma_f32_16x16x32_bf16 v[60:63], v[156:159], v[202:205], 0
	v_mfma_f32_16x16x32_bf16 v[48:51], v[132:135], v[210:213], 0
	v_mfma_f32_16x16x32_bf16 v[44:47], v[156:159], v[210:213], 0
	v_mfma_f32_16x16x32_bf16 v[30:33], v[132:135], v[218:221], 0
	v_mfma_f32_16x16x32_bf16 v[26:29], v[156:159], v[218:221], 0
	v_mfma_f32_16x16x32_bf16 v[14:17], v[132:135], v[234:237], 0
	v_mfma_f32_16x16x32_bf16 v[10:13], v[156:159], v[234:237], 0
	v_mfma_f32_16x16x32_bf16 v[64:67], v[136:139], v[206:209], v[64:67]
	v_mfma_f32_16x16x32_bf16 v[60:63], v[160:163], v[206:209], v[60:63]
	v_mfma_f32_16x16x32_bf16 v[48:51], v[136:139], v[214:217], v[48:51]
	v_mfma_f32_16x16x32_bf16 v[44:47], v[160:163], v[214:217], v[44:47]
	v_mfma_f32_16x16x32_bf16 v[30:33], v[136:139], v[222:225], v[30:33]
	v_mfma_f32_16x16x32_bf16 v[26:29], v[160:163], v[222:225], v[26:29]
	v_mfma_f32_16x16x32_bf16 v[14:17], v[136:139], v[238:241], v[14:17]
	v_mfma_f32_16x16x32_bf16 v[10:13], v[160:163], v[238:241], v[10:13]
	v_mfma_f32_16x16x32_bf16 v[56:59], v[186:189], v[202:205], 0
	v_mfma_f32_16x16x32_bf16 v[52:55], v[194:197], v[202:205], 0
	v_mfma_f32_16x16x32_bf16 v[40:43], v[186:189], v[210:213], 0
	v_mfma_f32_16x16x32_bf16 v[36:39], v[194:197], v[210:213], 0
	v_mfma_f32_16x16x32_bf16 v[22:25], v[186:189], v[218:221], 0
	v_mfma_f32_16x16x32_bf16 v[18:21], v[194:197], v[218:221], 0
	v_mfma_f32_16x16x32_bf16 v[6:9], v[186:189], v[234:237], 0
	v_mfma_f32_16x16x32_bf16 v[2:5], v[194:197], v[234:237], 0
	v_mfma_f32_16x16x32_bf16 v[56:59], v[190:193], v[206:209], v[56:59]
	v_mfma_f32_16x16x32_bf16 v[52:55], v[198:201], v[206:209], v[52:55]
	v_mfma_f32_16x16x32_bf16 v[40:43], v[190:193], v[214:217], v[40:43]
	v_mfma_f32_16x16x32_bf16 v[36:39], v[198:201], v[214:217], v[36:39]
	v_mfma_f32_16x16x32_bf16 v[22:25], v[190:193], v[222:225], v[22:25]
	v_mfma_f32_16x16x32_bf16 v[18:21], v[198:201], v[222:225], v[18:21]
	v_mfma_f32_16x16x32_bf16 v[6:9], v[190:193], v[238:241], v[6:9]
	v_mfma_f32_16x16x32_bf16 v[2:5], v[198:201], v[238:241], v[2:5]
	s_barrier
	s_branch .Lpeel_mid_923
	.p2align	6

; #define PG8_STAGE(bufoff, gbase, voff) do { _Pragma("unroll") for (int _i = 0; _i < 2; ++_i) \
;         __builtin_amdgcn_global_load_lds((const unsigned*)((const char*)(gbase) + (voff)[_i]), (PG8_LAS unsigned*)(lds + (bufoff) + ldsw + _i * 8192), 16, 0, 0); } while (0)
; #define PG8_LDA(dst, b, h) do { _Pragma("unroll") for (int m = 0; m < 4; ++m) _Pragma("unroll") for (int k = 0; k < 2; ++k) dst[m][k] = *(const PG8_LAS bf16x8*)(lds + PG8_SA(b, h) + aoff + m * 2048 + k * 1024); } while (0)
; #define PG8_LDB(dst, b, h) do { _Pragma("unroll") for (int n = 0; n < 2; ++n) _Pragma("unroll") for (int k = 0; k < 2; ++k) dst[n][k] = *(const PG8_LAS bf16x8*)(lds + PG8_SB(b, h) + boff + n * 2048 + k * 1024); } while (0)
; #define PG8_WAIT_V(n) asm volatile("s_waitcnt vmcnt(" #n ")" ::: "memory")
; #define PG8_WAIT_L(n) asm volatile("s_waitcnt lgkmcnt(" #n ")" ::: "memory")
; #define PG8_BAR __builtin_amdgcn_s_barrier()
; #define PG8_SCHED __builtin_amdgcn_sched_barrier(0)
;     ...
;             PG8_LDB(B0, 0, 0); PG8_LDB(B1, 0, 1); PG8_SCHED; PG8_LDA(At, 0, 0); PG8_STAGE(PG8_SA(1, 1), a1 + hstepA, voffA);
;             PG8_WAIT_V(8); PG8_WAIT_L(0); PG8_BAR; PG8_MMA(0, 0, At, B0); PG8_MMA(0, 1, At, B1); PG8_BAR; PG8_SCHED;
;             PG8_LDA(At, 0, 1); PG8_STAGE(PG8_SB(0, 0), b2, voffB); PG8_STAGE(PG8_SB(0, 1), b2 + hstepB, voffB); PG8_STAGE(PG8_SA(0, 0), a2, voffA);
;             PG8_WAIT_V(8); PG8_WAIT_L(0); PG8_BAR; PG8_MMA(1, 0, At, B0); PG8_MMA(1, 1, At, B1); PG8_BAR; PG8_SCHED;
.LBB0_1152:
	s_ashr_i32 s49, s48, 31
	s_lshl_b64 s[10:11], s[48:49], 20
	s_add_u32 s50, s60, s10
	s_addc_u32 s51, s61, s11
	s_and_b64 s[10:11], s[38:39], exec
	s_cselect_b32 s6, s51, s27
	s_cselect_b32 s10, s50, s26
	s_ashr_i32 s19, s18, 31
	s_lshl_b64 s[12:13], s[18:19], 20
	s_add_u32 s52, s62, s12
	s_addc_u32 s53, s63, s13
	s_and_b64 s[12:13], s[38:39], exec
	s_cselect_b32 s11, s53, s41
	s_cselect_b32 s12, s52, s40
	s_add_u32 s26, s26, 0x80080
	s_addc_u32 s27, s27, 0
	s_add_u32 s13, s40, 0x100
	s_addc_u32 s15, s41, 0
	s_mov_b32 s19, -2
	v_add_u32_e32 v162, 0x10000, v155
	s_add_u32 s34, s26, 0xfff80080
	s_addc_u32 s35, s27, -1
	s_add_i32 s37, 0, 0x10000
	s_cmp_eq_u32 s19, 28
	s_cselect_b32 s57, s6, s35
	s_cselect_b32 s56, s10, s34
	s_cselect_b32 s41, s11, s15
	s_cselect_b32 s40, s12, s13
	s_add_i32 s49, 0, 0x14000
	ds_read_b128 v[132:135], v162
	ds_read_b128 v[136:139], v162 offset:1024
	s_waitcnt vmcnt(6)
	ds_read_b128 v[158:161], v162 offset:2048
	ds_read_b128 v[186:189], v162 offset:3072
	ds_read_b128 v[190:193], v162 offset:16384
	ds_read_b128 v[194:197], v162 offset:17408
	ds_read_b128 v[198:201], v162 offset:18432
	ds_read_b128 v[202:205], v162 offset:19456
	s_add_i32 m0, s8, 0xc000
	ds_read_b128 v[206:209], v157
	ds_read_b128 v[210:213], v157 offset:1024
	ds_read_b128 v[214:217], v157 offset:2048
	ds_read_b128 v[218:221], v157 offset:3072
	ds_read_b128 v[222:225], v157 offset:4096
	ds_read_b128 v[234:237], v157 offset:5120
	ds_read_b128 v[238:241], v157 offset:6144
	ds_read_b128 v[242:245], v157 offset:7168
	global_load_lds_dwordx4 v150, s[26:27]
	s_add_i32 m0, s8, 0xe000
	s_nop 0
	global_load_lds_dwordx4 v152, s[26:27]
	s_waitcnt vmcnt(8)
	s_waitcnt lgkmcnt(0)
	s_barrier
	v_mfma_f32_16x16x32_bf16 v[128:131], v[132:135], v[206:209], 0
	v_mfma_f32_16x16x32_bf16 v[124:127], v[158:161], v[206:209], 0
	v_mfma_f32_16x16x32_bf16 v[112:115], v[132:135], v[214:217], 0
	v_mfma_f32_16x16x32_bf16 v[108:111], v[158:161], v[214:217], 0
	v_mfma_f32_16x16x32_bf16 v[96:99], v[132:135], v[222:225], 0
	v_mfma_f32_16x16x32_bf16 v[92:95], v[158:161], v[222:225], 0
	v_mfma_f32_16x16x32_bf16 v[80:83], v[132:135], v[238:241], 0
	v_mfma_f32_16x16x32_bf16 v[76:79], v[158:161], v[238:241], 0
	v_mfma_f32_16x16x32_bf16 v[128:131], v[136:139], v[210:213], v[128:131]
	v_mfma_f32_16x16x32_bf16 v[124:127], v[186:189], v[210:213], v[124:127]
	v_mfma_f32_16x16x32_bf16 v[112:115], v[136:139], v[218:221], v[112:115]
	v_mfma_f32_16x16x32_bf16 v[108:111], v[186:189], v[218:221], v[108:111]
	v_mfma_f32_16x16x32_bf16 v[96:99], v[136:139], v[234:237], v[96:99]
	v_mfma_f32_16x16x32_bf16 v[92:95], v[186:189], v[234:237], v[92:95]
	v_mfma_f32_16x16x32_bf16 v[80:83], v[136:139], v[242:245], v[80:83]
	v_mfma_f32_16x16x32_bf16 v[76:79], v[186:189], v[242:245], v[76:79]
	v_mfma_f32_16x16x32_bf16 v[120:123], v[190:193], v[206:209], 0
	v_mfma_f32_16x16x32_bf16 v[116:119], v[198:201], v[206:209], 0
	v_mfma_f32_16x16x32_bf16 v[104:107], v[190:193], v[214:217], 0
	v_mfma_f32_16x16x32_bf16 v[100:103], v[198:201], v[214:217], 0
	v_mfma_f32_16x16x32_bf16 v[88:91], v[190:193], v[222:225], 0
	v_mfma_f32_16x16x32_bf16 v[84:87], v[198:201], v[222:225], 0
	v_mfma_f32_16x16x32_bf16 v[72:75], v[190:193], v[238:241], 0
	v_mfma_f32_16x16x32_bf16 v[68:71], v[198:201], v[238:241], 0
	v_mfma_f32_16x16x32_bf16 v[120:123], v[194:197], v[210:213], v[120:123]
	v_mfma_f32_16x16x32_bf16 v[116:119], v[202:205], v[210:213], v[116:119]
	v_mfma_f32_16x16x32_bf16 v[104:107], v[194:197], v[218:221], v[104:107]
	v_mfma_f32_16x16x32_bf16 v[100:103], v[202:205], v[218:221], v[100:103]
	v_mfma_f32_16x16x32_bf16 v[88:91], v[194:197], v[234:237], v[88:91]
	v_mfma_f32_16x16x32_bf16 v[84:87], v[202:205], v[234:237], v[84:87]
	v_mfma_f32_16x16x32_bf16 v[72:75], v[194:197], v[242:245], v[72:75]
	v_mfma_f32_16x16x32_bf16 v[68:71], v[202:205], v[242:245], v[68:71]
	s_barrier
	s_add_i32 s34, s37, s7
	s_mov_b32 m0, s34
	ds_read_b128 v[206:209], v157 offset:16384
	ds_read_b128 v[210:213], v157 offset:17408
	ds_read_b128 v[214:217], v157 offset:18432
	ds_read_b128 v[218:221], v157 offset:19456
	ds_read_b128 v[222:225], v157 offset:20480
	ds_read_b128 v[234:237], v157 offset:21504
	ds_read_b128 v[238:241], v157 offset:22528
	ds_read_b128 v[242:245], v157 offset:23552
	global_load_lds_dwordx4 v142, s[40:41]
	s_add_i32 m0, s34, 0x2000
	s_add_u32 s34, s40, 0x80000
	s_addc_u32 s35, s41, 0
	s_add_i32 s37, s49, s7
	global_load_lds_dwordx4 v146, s[40:41]
	s_mov_b32 m0, s37
	s_nop 0
	global_load_lds_dwordx4 v142, s[34:35]
	s_add_i32 m0, s37, 0x2000
	s_nop 0
	global_load_lds_dwordx4 v146, s[34:35]
	s_mov_b32 m0, s8
	s_nop 0
	global_load_lds_dwordx4 v140, s[56:57]
	s_mov_b32 m0, s9
	s_nop 0
	global_load_lds_dwordx4 v144, s[56:57]
	s_waitcnt vmcnt(8)
	s_waitcnt lgkmcnt(0)
	s_barrier
	v_mfma_f32_16x16x32_bf16 v[64:67], v[132:135], v[206:209], 0
	v_mfma_f32_16x16x32_bf16 v[60:63], v[158:161], v[206:209], 0
	v_mfma_f32_16x16x32_bf16 v[48:51], v[132:135], v[214:217], 0
	v_mfma_f32_16x16x32_bf16 v[44:47], v[158:161], v[214:217], 0
	v_mfma_f32_16x16x32_bf16 v[30:33], v[132:135], v[222:225], 0
	v_mfma_f32_16x16x32_bf16 v[26:29], v[158:161], v[222:225], 0
	v_mfma_f32_16x16x32_bf16 v[14:17], v[132:135], v[238:241], 0
	v_mfma_f32_16x16x32_bf16 v[10:13], v[158:161], v[238:241], 0
	v_mfma_f32_16x16x32_bf16 v[64:67], v[136:139], v[210:213], v[64:67]
	v_mfma_f32_16x16x32_bf16 v[60:63], v[186:189], v[210:213], v[60:63]
	v_mfma_f32_16x16x32_bf16 v[48:51], v[136:139], v[218:221], v[48:51]
	v_mfma_f32_16x16x32_bf16 v[44:47], v[186:189], v[218:221], v[44:47]
	v_mfma_f32_16x16x32_bf16 v[30:33], v[136:139], v[234:237], v[30:33]
	v_mfma_f32_16x16x32_bf16 v[26:29], v[186:189], v[234:237], v[26:29]
	v_mfma_f32_16x16x32_bf16 v[14:17], v[136:139], v[242:245], v[14:17]
	v_mfma_f32_16x16x32_bf16 v[10:13], v[186:189], v[242:245], v[10:13]
	v_mfma_f32_16x16x32_bf16 v[56:59], v[190:193], v[206:209], 0
	v_mfma_f32_16x16x32_bf16 v[52:55], v[198:201], v[206:209], 0
	v_mfma_f32_16x16x32_bf16 v[40:43], v[190:193], v[214:217], 0
	v_mfma_f32_16x16x32_bf16 v[36:39], v[198:201], v[214:217], 0
	v_mfma_f32_16x16x32_bf16 v[22:25], v[190:193], v[222:225], 0
	v_mfma_f32_16x16x32_bf16 v[18:21], v[198:201], v[222:225], 0
	v_mfma_f32_16x16x32_bf16 v[6:9], v[190:193], v[238:241], 0
	v_mfma_f32_16x16x32_bf16 v[2:5], v[198:201], v[238:241], 0
	v_mfma_f32_16x16x32_bf16 v[56:59], v[194:197], v[210:213], v[56:59]
	v_mfma_f32_16x16x32_bf16 v[52:55], v[202:205], v[210:213], v[52:55]
	v_mfma_f32_16x16x32_bf16 v[40:43], v[194:197], v[218:221], v[40:43]
	v_mfma_f32_16x16x32_bf16 v[36:39], v[202:205], v[218:221], v[36:39]
	v_mfma_f32_16x16x32_bf16 v[22:25], v[194:197], v[234:237], v[22:25]
	v_mfma_f32_16x16x32_bf16 v[18:21], v[202:205], v[234:237], v[18:21]
	v_mfma_f32_16x16x32_bf16 v[6:9], v[194:197], v[242:245], v[6:9]
	v_mfma_f32_16x16x32_bf16 v[2:5], v[202:205], v[242:245], v[2:5]
	s_barrier
	s_branch .Lpeel_mid_1153
	.p2align	6
